# down GEMM takes its two tiles per workgroup in reverse order (most recently written half of U first: memory-side cache hits)
# speedup vs baseline: 1.0048x; 1.0048x over previous
; __device__ __forceinline__ int opaque_tid() { int t = threadIdx.x; asm volatile("" : "+v"(t)); return t; }
; #define PG8_STAGE(bufoff, gbase, voff) do { _Pragma("unroll") for (int _i = 0; _i < 2; ++_i) \
;         __builtin_amdgcn_global_load_lds((const unsigned*)((const char*)(gbase) + (voff)[_i]), (PG8_LAS unsigned*)(lds + (bufoff) + ldsw + _i * 8192), 16, 0, 0); } while (0)
; template <class Epi, class Sched, bool ALIGN_EPI = false, bool SP2 = false>
; __device__ __forceinline__ void gemm_phase(PG8_LAS unsigned char* lds, const Gemm g, const Sched& S, const Epi& E) {
;     const int tid = opaque_tid(), wid = __builtin_amdgcn_readfirstlane(tid >> 6), lane = tid & 63, wr = wid >> 2, wc = wid & 3, fr = lane & 15, fq = lane >> 4;
;     const int K = g.K, nt = K / BK;
;     unsigned voffA[2], voffB[2];
; #pragma unroll
;     for (int i = 0; i < 2; ++i) { int R, C; stage_rc(tid * 16 + i * 8192, R, C); const int Rb = Epi::PERM ? ((R & ~31) + perm32(R & 31)) : R;
;         voffA[i] = (unsigned)(R * K + C) * 2u; voffB[i] = (unsigned)(Rb * K + C) * 2u; }
;     const size_t kstep = (size_t)(BK * 2);
;     const size_t hstep = (size_t)HALF * K * 2;
;     const size_t tstep = 2 * hstep;
;     const unsigned ldsw = (unsigned)wid * 1024u;
;     const int aoff = lds_byte(wr * 64 + fr, fq * 8), boff = lds_byte(wc * 32 + fr, fq * 8);
;     ...
;     Unit cur, nxt; int ui = 0;
;     if (!S.next(0, cur)) return;
;     f32x4 acc[2][2][4][2];
; #pragma unroll
;     for (int a = 0; a < 2; ++a)
; #pragma unroll
;         for (int b = 0; b < 2; ++b)
; #pragma unroll
;             for (int m = 0; m < 4; ++m)
; #pragma unroll
;                 for (int n = 0; n < 2; ++n) acc[a][b][m][n] = (f32x4){0.f, 0.f, 0.f, 0.f};
;     bf16x8 At[4][2], B0[2][2], B1[2][2];
;     const char* cA = (const char*)g.A + (size_t)cur.pm * tstep; const char* cB = (const char*)g.Bt + (size_t)cur.pn * tstep;
;     S.a_ready(cur);
;     if constexpr (SP2) {
;         PG8_STAGE(PG8_SB(0, 0), cB, voffB); PG8_STAGE(PG8_SB(0, 1), cB + hstep, voffB); PG8_STAGE(PG8_SA(0, 0), cA, voffA); PG8_STAGE(PG8_SA(0, 1), cA + hstep, voffA);
;         if (wr == 1) PG8_BAR;
;         PG8_WAIT_V(2); PG8_BAR;
;         PG8_STAGE(PG8_SB(1, 0), cB + kstep, voffB); PG8_STAGE(PG8_SA(1, 0), cA + kstep, voffA); PG8_STAGE(PG8_SB(1, 1), cB + hstep + kstep, voffB);
;         PG8_WAIT_V(6); PG8_BAR;
.LBB0_1049:
	s_or_b64 exec, exec, s[8:9]
	v_readlane_b32 s2, v253, 8
	s_mov_b64 s[8:9], s[90:91]
	v_mov_b32_e32 v22, v194
	v_readlane_b32 s3, v253, 9
	s_waitcnt lgkmcnt(0)
	s_barrier
	s_andn2_b64 vcc, exec, s[2:3]
	v_readfirstlane_b32 s16, v22
	s_cbranch_vccnz .LBB0_1069
	v_lshlrev_b32_e32 v0, 4, v22
	v_add_u32_e32 v2, 0x2000, v0
	v_ashrrev_i32_e32 v3, 31, v2
	v_lshrrev_b32_e32 v3, 22, v3
	v_add_u32_e32 v3, v2, v3
	v_ashrrev_i32_e32 v10, 10, v3
	v_mul_i32_i24_e32 v3, 0x400, v10
	v_sub_u32_e32 v2, v2, v3
	v_lshrrev_b32_e32 v3, 4, v2
	v_bitop3_b32 v2, v3, v2, 32 bitop3:0x6c
	v_ashrrev_i32_e32 v3, 31, v2
	v_lshrrev_b32_e32 v3, 26, v3
	v_add_u32_e32 v3, v2, v3
	v_ashrrev_i32_e32 v11, 6, v3
	v_and_b32_e32 v3, 0xc0, v3
	v_sub_u32_e32 v2, v2, v3
	v_ashrrev_i16_sdwa v2, v250, sext(v2) dst_sel:DWORD dst_unused:UNUSED_PAD src0_sel:DWORD src1_sel:BYTE_0
	v_bfe_i32 v13, v2, 0, 16
	v_bfe_i32 v2, v22, 27, 1
	v_lshrrev_b32_e32 v2, 22, v2
	v_add_u32_e32 v2, v0, v2
	v_and_b32_e32 v2, 0xfffffc00, v2
	s_load_dwordx4 s[12:15], s[8:9], 0x80
	v_sub_u32_e32 v0, v0, v2
	v_lshrrev_b32_e32 v2, 4, v0
	v_bitop3_b32 v2, v2, v0, 32 bitop3:0x6c
	v_ashrrev_i32_e32 v0, 31, v0
	v_lshrrev_b32_e32 v0, 26, v0
	v_add_u32_e32 v0, v2, v0
	s_waitcnt lgkmcnt(0)
	s_add_u32 s2, s14, s10
	v_ashrrev_i32_e32 v18, 6, v0
	v_ashrrev_i32_e32 v0, 31, v22
	s_addc_u32 s3, s15, s11
	v_lshrrev_b32_e32 v0, 26, v0
	s_add_u32 s2, s2, 0x4300000
	v_add_u32_e32 v0, v22, v0
	s_addc_u32 s3, s3, 0
	v_ashrrev_i32_e32 v19, 6, v0
	s_add_u32 s4, s14, 0xa600000
	v_lshlrev_b32_e32 v3, 5, v19
	s_addc_u32 s5, s15, 0
	s_ashr_i32 s8, s16, 6
	v_lshlrev_b32_e32 v0, 3, v19
	v_and_b32_e32 v20, 32, v3
	v_mul_i32_i24_e32 v3, 64, v18
	s_ashr_i32 s9, s16, 8
	s_lshl_b32 s6, s8, 10
	v_and_b32_e32 v0, 0x7fff0, v0
	v_sub_u32_e32 v2, v2, v3
	v_readlane_b32 s14, v254, 0
	v_lshlrev_b32_e32 v4, 3, v10
	v_add_u32_e32 v0, v18, v0
	v_ashrrev_i16_sdwa v2, v250, sext(v2) dst_sel:DWORD dst_unused:UNUSED_PAD src0_sel:DWORD src1_sel:BYTE_0
	v_readlane_b32 s15, v254, 1
	s_add_u32 s28, s2, s14
	v_and_b32_e32 v4, 0x7fff0, v4
	v_lshlrev_b32_e32 v5, 5, v10
	v_lshl_or_b32 v0, v0, 12, v20
	v_bfe_i32 v21, v2, 0, 16
	s_addc_u32 s29, s3, s15
	s_add_i32 s33, s6, 0
	v_add_u32_e32 v4, v11, v4
	v_and_b32_e32 v12, 32, v5
	v_add_lshl_u32 v0, v0, v21, 1
	s_add_i32 m0, s33, 0x10000
	v_lshl_or_b32 v4, v4, 12, v12
	global_load_lds_dwordx4 v0, s[28:29]
	s_add_i32 m0, s33, 0x12000
	v_add_lshl_u32 v14, v4, v13, 1
	s_add_u32 s14, s28, 0x100000
	global_load_lds_dwordx4 v14, s[28:29]
	s_addc_u32 s15, s29, 0
	s_add_i32 m0, s33, 0x14000
	v_mov_b32_e32 v15, v1
	global_load_lds_dwordx4 v0, s[14:15]
	s_add_i32 m0, s33, 0x16000
	v_lshl_add_u64 v[8:9], s[28:29], 0, v[0:1]
	global_load_lds_dwordx4 v14, s[14:15]
	v_readlane_b32 s14, v253, 62
	v_readlane_b32 s15, v253, 63
	s_add_u32 s26, s4, s14
	s_addc_u32 s27, s5, s15
	s_add_u32 s26, s26, 0x1000000
	s_addc_u32 s27, s27, 0
	s_add_i32 s36, s33, 0x2000
	s_mov_b32 m0, s33
	s_add_u32 s14, s26, 0x100000
	global_load_lds_dwordx4 v0, s[26:27]
	s_mov_b32 m0, s36
	s_addc_u32 s15, s27, 0
	s_add_i32 s37, s33, 0x4000
	global_load_lds_dwordx4 v14, s[26:27]
	s_mov_b32 m0, s37
	s_add_i32 s38, s33, 0x6000
	global_load_lds_dwordx4 v0, s[14:15]
	s_mov_b32 m0, s38
	s_cmp_eq_u32 s9, 1
	global_load_lds_dwordx4 v14, s[14:15]
	v_lshl_add_u64 v[6:7], s[28:29], 0, v[14:15]
	v_lshl_add_u64 v[2:3], s[26:27], 0, v[0:1]
	s_cselect_b64 s[14:15], -1, 0
	s_cmp_lg_u32 s9, 1
	v_lshl_add_u64 v[4:5], s[26:27], 0, v[14:15]
	s_cbranch_scc1 .LBB0_1052
	s_barrier
.LBB0_1052:
	v_bfe_u32 v23, v22, 4, 2
	s_lshl_b32 s8, s8, 5
	v_and_b32_e32 v24, 15, v22
	v_lshlrev_b32_e32 v25, 4, v23
	v_lshlrev_b32_e32 v22, 2, v22
	s_and_b32 s18, s8, 0x60
	s_add_i32 m0, s33, 0x18000
	v_lshl_add_u64 v[8:9], v[8:9], 0, s[64:65]
	v_lshl_or_b32 v17, s9, 6, v24
	v_lshl_or_b32 v24, v24, 6, v25
	s_lshl_b32 s9, s9, 13
	v_and_b32_e32 v22, 32, v22
	s_lshl_b32 s8, s18, 7
	s_waitcnt vmcnt(2)
	s_barrier
	global_load_lds_dwordx4 v[8:9], off
	v_lshl_add_u64 v[6:7], v[6:7], 0, s[64:65]
	s_add_i32 m0, s33, 0x1a000
	s_add_i32 s39, s33, 0x8000
	s_add_i32 s40, s33, 0xa000
	v_bitop3_b32 v162, v24, s8, v22 bitop3:0xde
	global_load_lds_dwordx4 v[6:7], off
	v_lshl_add_u64 v[2:3], v[2:3], 0, s[64:65]
	s_mov_b32 m0, s39
	s_add_u32 s8, s28, 0x100080
	v_bitop3_b32 v25, v24, s9, v22 bitop3:0xde
	global_load_lds_dwordx4 v[2:3], off
	v_lshl_add_u64 v[2:3], v[4:5], 0, s[64:65]
	s_mov_b32 m0, s40
	s_addc_u32 s9, s29, 0
	global_load_lds_dwordx4 v[2:3], off
	s_add_i32 m0, s33, 0x1c000
	v_lshl_add_u64 v[2:3], s[8:9], 0, v[0:1]
	global_load_lds_dwordx4 v[2:3], off
	v_lshl_add_u64 v[2:3], s[8:9], 0, v[14:15]
	s_add_i32 m0, s33, 0x1e000
	s_mov_b64 s[8:9], 0x100080
	global_load_lds_dwordx4 v[2:3], off
	v_lshlrev_b32_e32 v2, 15, v19
	v_and_b32_e32 v2, 0x7fff0000, v2
	v_lshl_add_u32 v2, v18, 12, v2
	v_or_b32_e32 v2, v2, v20
	v_add_lshl_u32 v2, v2, v21, 1
	v_mov_b32_e32 v3, v1
	v_lshl_add_u64 v[138:139], v[2:3], 0, s[8:9]
	v_lshlrev_b32_e32 v2, 15, v10
	v_and_b32_e32 v2, 0x7fff0000, v2
	v_lshl_add_u32 v2, v11, 12, v2
	v_or_b32_e32 v2, v2, v12
	s_waitcnt vmcnt(6)
	v_add_lshl_u32 v2, v2, v13, 1
	s_cmpk_lt_u32 s16, 0x100
	v_lshl_add_u64 v[140:141], v[2:3], 0, s[8:9]
	v_readlane_b32 s8, v253, 60
	s_cselect_b64 s[16:17], -1, 0
	v_lshl_or_b32 v163, v23, 2, s18
	s_mov_b32 s41, 0
	v_add_u32_e32 v164, 0, v25
	v_readlane_b32 s42, v253, 48
	s_mov_b32 s43, s8
	s_add_i32 s43, s43, 8
	s_barrier
	v_readlane_b32 s9, v253, 61
	s_branch .LBB0_1055

;     __host__ __device__ bool next(int i, Unit& u) const {
;         const long L = (long)i * G + c; if (L >= nwg) return false;
;         int wgid = (int)L; { const int q = nwg / NXCD, r = nwg % NXCD, xcd = wgid % NXCD, off = wgid / NXCD; wgid = (xcd < r ? xcd * (q + 1) : r * (q + 1) + (xcd - r) * q) + off; }
;         const int nig = WGM * nN, gid = wgid / nig, fm = gid * WGM, gsz = (nM - fm) < WGM ? (nM - fm) : WGM;
;         u.pm = fm + ((wgid % nig) % gsz); u.pn = (wgid % nig) / gsz; return true;
; template <class Epi, class Sched, bool ALIGN_EPI = false, bool SP2 = false>
; __device__ __forceinline__ void gemm_phase(PG8_LAS unsigned char* lds, const Gemm g, const Sched& S, const Epi& E) {
;     ...
;         const bool has_next = S.next(ui + 1, nxt);
.LBB0_1055:
	s_add_i32 s41, s41, 1
	s_mul_i32 s8, s41, s95
	s_mul_hi_u32 s9, s41, s94
	s_add_i32 s9, s9, s8
	s_mul_i32 s8, s41, s94
	s_add_u32 s22, s8, s92
	s_addc_u32 s23, s9, s93
	s_cmp_eq_u32 s41, 1
	s_cselect_b32 s24, s94, 0
	s_sub_u32 s22, s22, s24
	s_subb_u32 s23, s23, 0
	v_cmp_gt_i64_e32 vcc, s[22:23], v[160:161]
	v_cmp_lt_i64_e64 s[8:9], s[22:23], v[158:159]
	s_cbranch_vccnz .LBB0_1061
	s_ashr_i32 s18, s22, 31
	s_lshr_b32 s18, s18, 29
	s_add_i32 s20, s22, s18
	s_and_b32 s18, s20, -8
	s_sub_i32 s21, s22, s18
	s_cmp_gt_i32 s21, -1
	s_mov_b64 s[18:19], -1
	s_cbranch_scc0 .LBB0_1058
	s_lshl_b32 s22, s21, 6
	s_mov_b64 s[18:19], 0
